# P5 GEMM unit loops: accumulator clears as 64-bit moves of inline 0 (64 instrs instead of 127 v_mov_b32), on top of v73
# speedup vs baseline: 1.0018x; 1.0018x over previous
;     __device__ __forceinline__ bool next(int i, Unit& u) const { if (i >= n) return false; u.pm = pm + i * dpm; u.pn = first + i * dpn; return true; }
; template <class Epi, class Sched, bool ALIGN_EPI = false, bool SP2 = false>
; __device__ __forceinline__ void gemm_phase(PG8_LAS unsigned char* lds, const Gemm g, const Sched& S, const Epi& E) {
;     ...
;         const bool has_next = S.next(ui + 1, nxt);
;         const char* nA = has_next ? (const char*)g.A + (size_t)nxt.pm * tstep : cA; const char* nB = has_next ? (const char*)g.Bt + (size_t)nxt.pn * tstep : cB;
;     ...
; #pragma unroll
;         for (int a = 0; a < 2; ++a)
; #pragma unroll
;             for (int b = 0; b < 2; ++b)
; #pragma unroll
;                 for (int m = 0; m < 4; ++m)
; #pragma unroll
;                     for (int n = 0; n < 2; ++n) acc[a][b][m][n] = (f32x4){0.f, 0.f, 0.f, 0.f};
.LBB0_832:
	s_mov_b32 s74, s73
	s_add_i32 s73, s73, 1
	s_cmp_lt_i32 s73, s33
	s_mov_b64 s[56:57], s[4:5]
	s_cselect_b64 s[66:67], -1, 0
	s_and_b64 s[4:5], s[12:13], exec
	s_cselect_b32 s4, s73, 0
	s_add_i32 s34, s4, s46
	s_and_b64 s[4:5], s[12:13], exec
	s_cselect_b32 s4, 0, s73
	s_add_i32 s35, s4, s80
	s_and_b64 s[4:5], s[66:67], exec
	s_mov_b32 s8, s60
	s_cselect_b32 s60, s34, s60
	s_mov_b32 s9, s58
	s_cselect_b32 s58, s35, s58
	s_ashr_i32 s61, s60, 31
	s_lshl_b64 s[4:5], s[60:61], 19
	s_add_u32 s4, s87, s4
	s_addc_u32 s5, s88, s5
	s_mov_b64 s[64:65], s[62:63]
	s_and_b64 s[62:63], s[66:67], exec
	s_cselect_b32 s50, s5, s57
	s_cselect_b32 s61, s4, s56
	s_ashr_i32 s59, s58, 31
	s_lshl_b64 s[62:63], s[58:59], 19
	s_add_u32 s62, s84, s62
	s_addc_u32 s63, s85, s63
	s_and_b64 s[66:67], s[66:67], exec
	s_cselect_b32 s59, s63, s65
	s_cselect_b32 s75, s62, s64
	s_add_u32 s56, s56, 0x40080
	s_addc_u32 s57, s57, 0
	s_add_u32 s77, s64, 0x100
	v_mov_b32_e32 v2, 0
	s_addc_u32 s78, s65, 0
	s_mov_b32 s81, -2
	v_mov_b64_e32 v[2:3], 0
	v_mov_b64_e32 v[4:5], 0
	v_mov_b64_e32 v[6:7], 0
	v_mov_b64_e32 v[8:9], 0
	v_mov_b64_e32 v[10:11], 0
	v_mov_b64_e32 v[12:13], 0
	v_mov_b64_e32 v[14:15], 0
	v_mov_b64_e32 v[16:17], 0
	v_mov_b64_e32 v[18:19], 0
	v_mov_b64_e32 v[20:21], 0
	v_mov_b64_e32 v[22:23], 0
	v_mov_b64_e32 v[24:25], 0
	v_mov_b64_e32 v[26:27], 0
	v_mov_b64_e32 v[28:29], 0
	v_mov_b64_e32 v[30:31], 0
	v_mov_b64_e32 v[32:33], 0
	v_mov_b64_e32 v[34:35], 0
	v_mov_b64_e32 v[36:37], 0
	v_mov_b64_e32 v[38:39], 0
	v_mov_b64_e32 v[40:41], 0
	v_mov_b64_e32 v[42:43], 0
	v_mov_b64_e32 v[44:45], 0
	v_mov_b64_e32 v[46:47], 0
	v_mov_b64_e32 v[48:49], 0
	v_mov_b64_e32 v[50:51], 0
	v_mov_b64_e32 v[52:53], 0
	v_mov_b64_e32 v[54:55], 0
	v_mov_b64_e32 v[56:57], 0
	v_mov_b64_e32 v[58:59], 0
	v_mov_b64_e32 v[60:61], 0
	v_mov_b64_e32 v[62:63], 0
	v_mov_b64_e32 v[64:65], 0
	v_mov_b64_e32 v[66:67], 0
	v_mov_b64_e32 v[68:69], 0
	v_mov_b64_e32 v[70:71], 0
	v_mov_b64_e32 v[72:73], 0
	v_mov_b64_e32 v[74:75], 0
	v_mov_b64_e32 v[76:77], 0
	v_mov_b64_e32 v[78:79], 0
	v_mov_b64_e32 v[80:81], 0
	v_mov_b64_e32 v[82:83], 0
	v_mov_b64_e32 v[84:85], 0
	v_mov_b64_e32 v[86:87], 0
	v_mov_b64_e32 v[88:89], 0
	v_mov_b64_e32 v[90:91], 0
	v_mov_b64_e32 v[92:93], 0
	v_mov_b64_e32 v[94:95], 0
	v_mov_b64_e32 v[96:97], 0
	v_mov_b64_e32 v[98:99], 0
	v_mov_b64_e32 v[100:101], 0
	v_mov_b64_e32 v[102:103], 0
	v_mov_b64_e32 v[104:105], 0
	v_mov_b64_e32 v[106:107], 0
	v_mov_b64_e32 v[108:109], 0
	v_mov_b64_e32 v[110:111], 0
	v_mov_b64_e32 v[112:113], 0
	v_mov_b64_e32 v[114:115], 0
	v_mov_b64_e32 v[116:117], 0
	v_mov_b64_e32 v[118:119], 0
	v_mov_b64_e32 v[120:121], 0
	v_mov_b64_e32 v[122:123], 0
	v_mov_b64_e32 v[124:125], 0
	v_mov_b64_e32 v[126:127], 0
	v_mov_b64_e32 v[128:129], 0

; template <class Epi, class Sched, bool ALIGN_EPI = false, bool SP2 = false>
; __device__ __forceinline__ void gemm_phase(PG8_LAS unsigned char* lds, const Gemm g, const Sched& S, const Epi& E) {
;     ...
;     f32x4 acc[2][2][4][2];
; #pragma unroll
;     for (int a = 0; a < 2; ++a)
; #pragma unroll
;         for (int b = 0; b < 2; ++b)
; #pragma unroll
;             for (int m = 0; m < 4; ++m)
; #pragma unroll
;                 for (int n = 0; n < 2; ++n) acc[a][b][m][n] = (f32x4){0.f, 0.f, 0.f, 0.f};
;     ...
; #pragma unroll
;         for (int a = 0; a < 2; ++a)
; #pragma unroll
;             for (int b = 0; b < 2; ++b)
; #pragma unroll
;                 for (int m = 0; m < 4; ++m)
; #pragma unroll
;                     for (int n = 0; n < 2; ++n) acc[a][b][m][n] = (f32x4){0.f, 0.f, 0.f, 0.f};
.LBB0_850:
	v_mov_b32_e32 v129, 0
	s_andn2_b64 vcc, exec, s[60:61]
	v_mov_b32_e32 v128, v129
	v_mov_b32_e32 v127, v129
	v_mov_b32_e32 v126, v129
	v_mov_b32_e32 v125, v129
	v_mov_b32_e32 v124, v129
	v_mov_b32_e32 v123, v129
	v_mov_b32_e32 v122, v129
	v_mov_b32_e32 v113, v129
	v_mov_b32_e32 v112, v129
	v_mov_b32_e32 v111, v129
	v_mov_b32_e32 v110, v129
	v_mov_b32_e32 v109, v129
	v_mov_b32_e32 v108, v129
	v_mov_b32_e32 v107, v129
	v_mov_b32_e32 v106, v129
	v_mov_b32_e32 v97, v129
	v_mov_b32_e32 v96, v129
	v_mov_b32_e32 v95, v129
	v_mov_b32_e32 v94, v129
	v_mov_b32_e32 v93, v129
	v_mov_b32_e32 v92, v129
	v_mov_b32_e32 v91, v129
	v_mov_b32_e32 v90, v129
	v_mov_b32_e32 v81, v129
	v_mov_b32_e32 v80, v129
	v_mov_b32_e32 v79, v129
	v_mov_b32_e32 v78, v129
	v_mov_b32_e32 v77, v129
	v_mov_b32_e32 v76, v129
	v_mov_b32_e32 v75, v129
	v_mov_b32_e32 v74, v129
	v_mov_b32_e32 v121, v129
	v_mov_b32_e32 v120, v129
	v_mov_b32_e32 v119, v129
	v_mov_b32_e32 v118, v129
	v_mov_b32_e32 v117, v129
	v_mov_b32_e32 v116, v129
	v_mov_b32_e32 v115, v129
	v_mov_b32_e32 v114, v129
	v_mov_b32_e32 v105, v129
	v_mov_b32_e32 v104, v129
	v_mov_b32_e32 v103, v129
	v_mov_b32_e32 v102, v129
	v_mov_b32_e32 v101, v129
	v_mov_b32_e32 v100, v129
	v_mov_b32_e32 v99, v129
	v_mov_b32_e32 v98, v129
	v_mov_b32_e32 v89, v129
	v_mov_b32_e32 v88, v129
	v_mov_b32_e32 v87, v129
	v_mov_b32_e32 v86, v129
	v_mov_b32_e32 v85, v129
	v_mov_b32_e32 v84, v129
	v_mov_b32_e32 v83, v129
	v_mov_b32_e32 v82, v129
	v_mov_b32_e32 v73, v129
	v_mov_b32_e32 v72, v129
	v_mov_b32_e32 v71, v129
	v_mov_b32_e32 v70, v129
	v_mov_b32_e32 v69, v129
	v_mov_b32_e32 v68, v129
	v_mov_b32_e32 v67, v129
	v_mov_b32_e32 v66, v129
	v_mov_b32_e32 v65, v129
	v_mov_b32_e32 v64, v129
	v_mov_b32_e32 v63, v129
	v_mov_b32_e32 v62, v129
	v_mov_b32_e32 v61, v129
	v_mov_b32_e32 v60, v129
	v_mov_b32_e32 v59, v129
	v_mov_b32_e32 v58, v129
	v_mov_b32_e32 v49, v129
	v_mov_b32_e32 v48, v129
	v_mov_b32_e32 v47, v129
	v_mov_b32_e32 v46, v129
	v_mov_b32_e32 v45, v129
	v_mov_b32_e32 v44, v129
	v_mov_b32_e32 v43, v129
	v_mov_b32_e32 v42, v129
	v_mov_b32_e32 v33, v129
	v_mov_b32_e32 v32, v129
	v_mov_b32_e32 v31, v129
	v_mov_b32_e32 v30, v129
	v_mov_b32_e32 v29, v129
	v_mov_b32_e32 v28, v129
	v_mov_b32_e32 v27, v129
	v_mov_b32_e32 v26, v129
	v_mov_b32_e32 v17, v129
	v_mov_b32_e32 v16, v129
	v_mov_b32_e32 v15, v129
	v_mov_b32_e32 v14, v129
	v_mov_b32_e32 v13, v129
	v_mov_b32_e32 v12, v129
	v_mov_b32_e32 v11, v129
	v_mov_b32_e32 v10, v129
	v_mov_b32_e32 v57, v129
	v_mov_b32_e32 v56, v129
	v_mov_b32_e32 v55, v129
	v_mov_b32_e32 v54, v129
	v_mov_b32_e32 v53, v129
	v_mov_b32_e32 v52, v129
	v_mov_b32_e32 v51, v129
	v_mov_b32_e32 v50, v129
	v_mov_b32_e32 v41, v129
	v_mov_b32_e32 v40, v129
	v_mov_b32_e32 v39, v129
	v_mov_b32_e32 v38, v129
	v_mov_b32_e32 v37, v129
	v_mov_b32_e32 v36, v129
	v_mov_b32_e32 v35, v129
	v_mov_b32_e32 v34, v129
	v_mov_b32_e32 v25, v129
	v_mov_b32_e32 v24, v129
	v_mov_b32_e32 v23, v129
	v_mov_b32_e32 v22, v129
	v_mov_b32_e32 v21, v129
	v_mov_b32_e32 v20, v129
	v_mov_b32_e32 v19, v129
	v_mov_b32_e32 v18, v129
	v_mov_b32_e32 v9, v129
	v_mov_b32_e32 v8, v129
	v_mov_b32_e32 v7, v129
	v_mov_b32_e32 v6, v129
	v_mov_b32_e32 v5, v129
	v_mov_b32_e32 v4, v129
	v_mov_b32_e32 v3, v129
	v_mov_b32_e32 v2, v129
	s_cbranch_vccnz .LBB0_853
	s_add_u32 s56, s56, 0x80
	s_addc_u32 s57, s57, 0
	s_add_u32 vcc_lo, s74, 0x100
	v_mov_b32_e32 v2, 0
	s_addc_u32 vcc_hi, s75, 0
	s_mov_b32 s74, 0
	v_mov_b64_e32 v[2:3], 0
	v_mov_b64_e32 v[4:5], 0
	v_mov_b64_e32 v[6:7], 0
	v_mov_b64_e32 v[8:9], 0
	v_mov_b64_e32 v[10:11], 0
	v_mov_b64_e32 v[12:13], 0
	v_mov_b64_e32 v[14:15], 0
	v_mov_b64_e32 v[16:17], 0
	v_mov_b64_e32 v[18:19], 0
	v_mov_b64_e32 v[20:21], 0
	v_mov_b64_e32 v[22:23], 0
	v_mov_b64_e32 v[24:25], 0
	v_mov_b64_e32 v[26:27], 0
	v_mov_b64_e32 v[28:29], 0
	v_mov_b64_e32 v[30:31], 0
	v_mov_b64_e32 v[32:33], 0
	v_mov_b64_e32 v[34:35], 0
	v_mov_b64_e32 v[36:37], 0
	v_mov_b64_e32 v[38:39], 0
	v_mov_b64_e32 v[40:41], 0
	v_mov_b64_e32 v[42:43], 0
	v_mov_b64_e32 v[44:45], 0
	v_mov_b64_e32 v[46:47], 0
	v_mov_b64_e32 v[48:49], 0
	v_mov_b64_e32 v[50:51], 0
	v_mov_b64_e32 v[52:53], 0
	v_mov_b64_e32 v[54:55], 0
	v_mov_b64_e32 v[56:57], 0
	v_mov_b64_e32 v[58:59], 0
	v_mov_b64_e32 v[60:61], 0
	v_mov_b64_e32 v[62:63], 0
	v_mov_b64_e32 v[64:65], 0
	v_mov_b64_e32 v[66:67], 0
	v_mov_b64_e32 v[68:69], 0
	v_mov_b64_e32 v[70:71], 0
	v_mov_b64_e32 v[72:73], 0
	v_mov_b64_e32 v[74:75], 0
	v_mov_b64_e32 v[76:77], 0
	v_mov_b64_e32 v[78:79], 0
	v_mov_b64_e32 v[80:81], 0
	v_mov_b64_e32 v[82:83], 0
	v_mov_b64_e32 v[84:85], 0
	v_mov_b64_e32 v[86:87], 0
	v_mov_b64_e32 v[88:89], 0
	v_mov_b64_e32 v[90:91], 0
	v_mov_b64_e32 v[92:93], 0
	v_mov_b64_e32 v[94:95], 0
	v_mov_b64_e32 v[96:97], 0
	v_mov_b64_e32 v[98:99], 0
	v_mov_b64_e32 v[100:101], 0
	v_mov_b64_e32 v[102:103], 0
	v_mov_b64_e32 v[104:105], 0
	v_mov_b64_e32 v[106:107], 0
	v_mov_b64_e32 v[108:109], 0
	v_mov_b64_e32 v[110:111], 0
	v_mov_b64_e32 v[112:113], 0
	v_mov_b64_e32 v[114:115], 0
	v_mov_b64_e32 v[116:117], 0
	v_mov_b64_e32 v[118:119], 0
	v_mov_b64_e32 v[120:121], 0
	v_mov_b64_e32 v[122:123], 0
	v_mov_b64_e32 v[124:125], 0
	v_mov_b64_e32 v[126:127], 0
	v_mov_b64_e32 v[128:129], 0

;     __device__ __forceinline__ bool next(int i, Unit& u) const { if (i >= n) return false; u.pm = pm + i * dpm; u.pn = first + i * dpn; return true; }
; template <class Epi, class Sched, bool ALIGN_EPI = false, bool SP2 = false>
; __device__ __forceinline__ void gemm_phase(PG8_LAS unsigned char* lds, const Gemm g, const Sched& S, const Epi& E) {
;     ...
;         const bool has_next = S.next(ui + 1, nxt);
;         const char* nA = has_next ? (const char*)g.A + (size_t)nxt.pm * tstep : cA; const char* nB = has_next ? (const char*)g.Bt + (size_t)nxt.pn * tstep : cB;
;     ...
; #pragma unroll
;         for (int a = 0; a < 2; ++a)
; #pragma unroll
;             for (int b = 0; b < 2; ++b)
; #pragma unroll
;                 for (int m = 0; m < 4; ++m)
; #pragma unroll
;                     for (int n = 0; n < 2; ++n) acc[a][b][m][n] = (f32x4){0.f, 0.f, 0.f, 0.f};
.LBB0_899:
	s_mov_b32 s23, s22
	s_add_i32 s22, s22, 1
	s_cmp_lt_i32 s22, s33
	s_mov_b64 s[34:35], s[4:5]
	s_cselect_b64 s[50:51], -1, 0
	s_and_b64 s[4:5], s[12:13], exec
	s_cselect_b32 s4, s22, 0
	s_add_i32 s9, s4, s46
	s_and_b64 s[4:5], s[12:13], exec
	s_cselect_b32 s4, 0, s22
	s_add_i32 s10, s4, s80
	s_and_b64 s[4:5], s[50:51], exec
	s_mov_b32 s2, s58
	s_cselect_b32 s58, s9, s58
	s_mov_b32 s8, s52
	s_cselect_b32 s52, s10, s52
	s_ashr_i32 s59, s58, 31
	s_lshl_b64 s[4:5], s[58:59], 19
	s_add_u32 s4, s14, s4
	s_addc_u32 s5, s15, s5
	s_and_b64 s[42:43], s[50:51], exec
	s_cselect_b32 s9, s5, s35
	s_cselect_b32 s42, s4, s34
	s_ashr_i32 s53, s52, 31
	s_lshl_b64 s[56:57], s[52:53], 19
	s_mov_b64 s[62:63], s[60:61]
	s_add_u32 s60, s91, s56
	s_addc_u32 s61, s92, s57
	s_and_b64 s[50:51], s[50:51], exec
	s_cselect_b32 s43, s61, s63
	s_cselect_b32 s50, s60, s62
	s_add_u32 s56, s34, 0x40080
	s_addc_u32 s57, s35, 0
	s_add_u32 s51, s62, 0x100
	v_mov_b32_e32 v2, 0
	s_addc_u32 s53, s63, 0
	s_mov_b32 s59, -2
	v_mov_b64_e32 v[2:3], 0
	v_mov_b64_e32 v[4:5], 0
	v_mov_b64_e32 v[6:7], 0
	v_mov_b64_e32 v[8:9], 0
	v_mov_b64_e32 v[10:11], 0
	v_mov_b64_e32 v[12:13], 0
	v_mov_b64_e32 v[14:15], 0
	v_mov_b64_e32 v[16:17], 0
	v_mov_b64_e32 v[18:19], 0
	v_mov_b64_e32 v[20:21], 0
	v_mov_b64_e32 v[22:23], 0
	v_mov_b64_e32 v[24:25], 0
	v_mov_b64_e32 v[30:31], 0
	v_mov_b64_e32 v[32:33], 0
	v_mov_b64_e32 v[34:35], 0
	v_mov_b64_e32 v[36:37], 0
	v_mov_b64_e32 v[42:43], 0
	v_mov_b64_e32 v[44:45], 0
	v_mov_b64_e32 v[46:47], 0
	v_mov_b64_e32 v[48:49], 0
	v_mov_b64_e32 v[50:51], 0
	v_mov_b64_e32 v[52:53], 0
	v_mov_b64_e32 v[54:55], 0
	v_mov_b64_e32 v[56:57], 0
	v_mov_b64_e32 v[58:59], 0
	v_mov_b64_e32 v[60:61], 0
	v_mov_b64_e32 v[62:63], 0
	v_mov_b64_e32 v[64:65], 0
	v_mov_b64_e32 v[66:67], 0
	v_mov_b64_e32 v[68:69], 0
	v_mov_b64_e32 v[70:71], 0
	v_mov_b64_e32 v[72:73], 0
	v_mov_b64_e32 v[74:75], 0
	v_mov_b64_e32 v[76:77], 0
	v_mov_b64_e32 v[78:79], 0
	v_mov_b64_e32 v[80:81], 0
	v_mov_b64_e32 v[82:83], 0
	v_mov_b64_e32 v[84:85], 0
	v_mov_b64_e32 v[86:87], 0
	v_mov_b64_e32 v[88:89], 0
	v_mov_b64_e32 v[90:91], 0
	v_mov_b64_e32 v[92:93], 0
	v_mov_b64_e32 v[94:95], 0
	v_mov_b64_e32 v[96:97], 0
	v_mov_b64_e32 v[98:99], 0
	v_mov_b64_e32 v[100:101], 0
	v_mov_b64_e32 v[102:103], 0
	v_mov_b64_e32 v[104:105], 0
	v_mov_b64_e32 v[106:107], 0
	v_mov_b64_e32 v[108:109], 0
	v_mov_b64_e32 v[110:111], 0
	v_mov_b64_e32 v[112:113], 0
	v_mov_b64_e32 v[114:115], 0
	v_mov_b64_e32 v[116:117], 0
	v_mov_b64_e32 v[118:119], 0
	v_mov_b64_e32 v[120:121], 0
	v_mov_b64_e32 v[122:123], 0
	v_mov_b64_e32 v[124:125], 0
	v_mov_b64_e32 v[126:127], 0
	v_mov_b64_e32 v[128:129], 0
	v_mov_b64_e32 v[130:131], 0
	v_mov_b64_e32 v[132:133], 0
	v_mov_b64_e32 v[134:135], 0
	v_mov_b64_e32 v[136:137], 0
